# FoX fast path: packed f32 add beside MFMAs split into two scalar adds
# baseline (speedup 1.0000x reference)
; DEVI float opq(float x) { asm("" : "+v"(x)); return x; }
; template <int DK, int MODE, int RBM, class SF, class FF, class POST>
; DEVI void attn_tile_body(const bf16x8 (&qf)[2][DK / 32], const char* Ks, const char* Vs, SF& sf, FF& ff, POST& post,
;                          int cur, int c0, int c1, float (&m)[2], float (&l)[2], f32x4 (&o)[5][2], int fr, int fq) {
;     ...
;   for (int ks = 0; ks < NKC; ++ks)
; #pragma unroll
;     for (int kb = 0; kb < 4; ++kb) {
;       const int koff = DK == 64 ? (kb * 16 + fr) * 128 + (((ks * 4 + fq) ^ (fr & 7)) * 16)
;                                 : (kb * 16 + fr) * 192 + ((ks * 4 + (fq ^ ((fr >> 2) & 3))) * 16);
;       bf16x8 kf = *(const bf16x8*)(Ks + koff);
;       if (RBM & 1) s[kb][0] = __builtin_amdgcn_mfma_f32_16x16x32_bf16(kf, qf[0][ks], s[kb][0], 0, 0, 0);
;       if (RBM & 2) s[kb][1] = __builtin_amdgcn_mfma_f32_16x16x32_bf16(kf, qf[1][ks], s[kb][1], 0, 0, 0);
;     }
; #pragma unroll
;   for (int rb = 0; rb < 2; ++rb) {
;     if (!(RBM & (1 << rb))) continue;
;     const int cm = rb == 0 ? c0 : c1;
;     if (cm == 2) {
;       const float cl = ff.cl(rb, cur);
;       const float fsc = ff.sc;
;       if (FF::HASVEC) {
; #pragma unroll
;         for (int kb = 0; kb < 4; ++kb) {
;           const f32x4 av = ff.vec(kb);
; #pragma unroll
;           for (int j = 0; j < 4; ++j) s[kb][rb][j] = opq(fmaf(s[kb][rb][j], fsc, av[j]));
;         }
;       }
;       if (MODE == 2) {
;         const float c = cl - m[rb];
; #pragma unroll
;         for (int kb = 0; kb < 4; ++kb)
; #pragma unroll
;           for (int j = 0; j < 4; ++j) {
;             const float e = FF::HASVEC ? opq(s[kb][rb][j] + c) : opq(fmaf(s[kb][rb][j], fsc, c));
;             s[kb][rb][j] = opq(fexp2(e) * l[rb]);
;           }
;       } else if (MODE == 0) {
;         float mx = max16(s[0][rb], s[1][rb], s[2][rb], s[3][rb]);
;         mx = xmax16(mx); mx = xmax32(mx);
;         const float cand = FF::HASVEC ? (mx + cl) : fmaf(mx, fsc, cl);
;         if (__builtin_amdgcn_ballot_w64(cand > m[rb] + DEFER_THR) != 0) {
;           const float mn = fmaxf(m[rb], cand);
;           const float alpha = fexp2(m[rb] - mn);
;           m[rb] = mn;
; #pragma unroll
;           for (int db = 0; db < 5; ++db)
; #pragma unroll
;             for (int j = 0; j < 4; ++j) o[db][rb][j] = opq(o[db][rb][j] * alpha);
;         }
.LBB0_539:
	s_or_b64 exec, exec, s[54:55]
	v_lshrrev_b64 v[2:3], v60, v[118:119]
	s_and_b64 s[6:7], exec, vcc
	v_and_b32_e32 v2, 1, v2
	s_or_b64 s[52:53], s[6:7], s[52:53]
	v_cmp_eq_u32_e32 vcc, 1, v2
	s_and_saveexec_b64 s[38:39], vcc
	s_cbranch_execz .LBB0_557
	v_lshlrev_b32_e32 v197, 6, v60
	s_mul_i32 s6, s42, 0x4100
	v_or_b32_e32 v2, 63, v197
	v_cmp_le_i32_e32 vcc, v2, v113
	v_add_u32_e32 v2, s6, v115
	v_add_u32_e32 v3, v2, v123
	ds_read_b128 v[72:75], v3 offset:4096
	ds_read_b128 v[60:63], v3
	v_add_u32_e32 v2, v2, v134
	ds_read_b128 v[68:71], v3 offset:2048
	s_waitcnt lgkmcnt(0)
	v_mfma_f32_16x16x32_bf16 v[80:83], v[72:75], v[8:11], 0
	v_mfma_f32_16x16x32_bf16 v[144:147], v[72:75], v[16:19], 0
	ds_read_b128 v[72:75], v3 offset:6144
	s_waitcnt lgkmcnt(0)
	v_mfma_f32_16x16x32_bf16 v[148:151], v[72:75], v[8:11], 0
	v_mfma_f32_16x16x32_bf16 v[192:195], v[72:75], v[16:19], 0
	ds_read_b128 v[72:75], v2
	v_mfma_f32_16x16x32_bf16 v[64:67], v[60:63], v[8:11], 0
	v_mfma_f32_16x16x32_bf16 v[60:63], v[60:63], v[16:19], 0
	s_waitcnt lgkmcnt(0)
	v_mfma_f32_16x16x32_bf16 v[92:95], v[72:75], v[4:7], v[64:67]
	v_mfma_f32_16x16x32_bf16 v[72:75], v[72:75], v[12:15], v[60:63]
	s_nop 4
	ds_read_b128 v[60:63], v2 offset:2048
	v_mfma_f32_16x16x32_bf16 v[76:79], v[68:71], v[8:11], 0
	v_mfma_f32_16x16x32_bf16 v[68:71], v[68:71], v[16:19], 0
	s_waitcnt lgkmcnt(0)
	v_mfma_f32_16x16x32_bf16 v[88:91], v[60:63], v[4:7], v[76:79]
	v_mfma_f32_16x16x32_bf16 v[68:71], v[60:63], v[12:15], v[68:71]
	ds_read_b128 v[60:63], v2 offset:4096
	s_waitcnt lgkmcnt(0)
	v_mfma_f32_16x16x32_bf16 v[84:87], v[60:63], v[4:7], v[80:83]
	v_mfma_f32_16x16x32_bf16 v[64:67], v[60:63], v[12:15], v[144:147]
	ds_read_b128 v[60:63], v2 offset:6144
	s_waitcnt lgkmcnt(0)
	v_mfma_f32_16x16x32_bf16 v[80:83], v[60:63], v[4:7], v[148:151]
	v_add_u32_e32 v144, s6, v106
	v_mfma_f32_16x16x32_bf16 v[60:63], v[60:63], v[12:15], v[192:195]
	s_and_saveexec_b64 s[54:55], vcc
	s_xor_b64 s[54:55], exec, s[54:55]
	s_cbranch_execz .LBB0_544
	ds_read_b128 v[76:79], v144 offset:16384
	ds_read_b128 v[148:151], v144 offset:16576
	s_waitcnt lgkmcnt(0)
	v_fma_f32 v146, v92, s101, -v76
	v_fma_f32 v145, v93, s101, -v77
	v_fma_f32 v93, v94, s101, -v78
	v_fma_f32 v92, v95, s101, -v79
	ds_read_b128 v[76:79], v144 offset:16448
	s_waitcnt lgkmcnt(0)
	v_fma_f32 v94, v88, s101, -v76
	v_fma_f32 v88, v89, s101, -v77
	v_fma_f32 v89, v90, s101, -v78
	v_fma_f32 v90, v91, s101, -v79
	s_waitcnt vmcnt(0)
	ds_read_b128 v[76:79], v144 offset:16512
	v_max_f32_e32 v2, v145, v145
	v_max_f32_e32 v3, v146, v146
	s_waitcnt lgkmcnt(0)
	v_fma_f32 v91, v85, s101, -v77
	v_fma_f32 v85, v86, s101, -v78
	v_fma_f32 v86, v80, s101, -v148
	v_fma_f32 v95, v84, s101, -v76
	v_fma_f32 v80, v81, s101, -v149
	v_fma_f32 v84, v87, s101, -v79
	v_fma_f32 v81, v82, s101, -v150
	v_fma_f32 v82, v83, s101, -v151
	v_max_f32_e32 v2, v3, v2
	v_max3_f32 v3, v92, v94, v88
	v_max3_f32 v83, v91, v85, v84
	v_max3_f32 v87, v86, v80, v81
	s_nop 0
	v_max3_f32 v76, v89, v90, v95
	v_max3_f32 v2, v2, v93, v3
	v_max3_f32 v3, v83, v87, v82
	v_max3_f32 v2, v2, v76, v3
	v_mov_b32_e32 v3, v2
	s_nop 1
	v_permlane16_swap_b32_e32 v2, v3
	v_max_f32_e32 v2, v2, v3
	v_mov_b32_e32 v3, v2
	s_nop 1
	v_permlane32_swap_b32_e32 v2, v3
	v_max_f32_e32 v124, v2, v3
	v_add_f32_e32 v2, v108, v124
	v_add_f32_e32 v3, v109, v125
	v_cmp_gt_f32_e32 vcc, v2, v3
	s_cbranch_vccz .LBB0_543
	v_max_f32_e32 v3, v109, v109
	v_max_f32_e32 v2, v3, v2
	v_sub_f32_e32 v3, v109, v2
	v_exp_f32_e32 v3, v3
	v_mov_b32_e32 v109, v2
	v_mul_f32_e32 v56, v56, v3
	v_mul_f32_e32 v57, v57, v3
	v_mul_f32_e32 v58, v58, v3
	v_mul_f32_e32 v59, v59, v3
	v_mul_f32_e32 v52, v52, v3
	v_mul_f32_e32 v53, v53, v3
	v_mul_f32_e32 v54, v54, v3
	v_mul_f32_e32 v55, v55, v3
	v_mul_f32_e32 v48, v48, v3
	v_mul_f32_e32 v49, v49, v3
	v_mul_f32_e32 v50, v50, v3
	v_mul_f32_e32 v51, v51, v3
	v_mul_f32_e32 v44, v44, v3
	v_mul_f32_e32 v45, v45, v3
	v_mul_f32_e32 v46, v46, v3
	v_mul_f32_e32 v47, v47, v3
	v_mul_f32_e32 v24, v24, v3
	v_mul_f32_e32 v25, v25, v3
	v_mul_f32_e32 v26, v26, v3
	v_mul_f32_e32 v27, v27, v3

; DEVI float opq(float x) { asm("" : "+v"(x)); return x; }
; DEVI float fexp2(float x) { return __builtin_amdgcn_exp2f(x); }
; template <int DK, int MODE, int RBM, class SF, class FF, class POST>
; DEVI void attn_tile_body(const bf16x8 (&qf)[2][DK / 32], const char* Ks, const char* Vs, SF& sf, FF& ff, POST& post,
;                          int cur, int c0, int c1, float (&m)[2], float (&l)[2], f32x4 (&o)[5][2], int fr, int fq) {
;     ...
;     if (cm == 2) {
;       const float cl = ff.cl(rb, cur);
;       const float fsc = ff.sc;
;       if (FF::HASVEC) {
; #pragma unroll
;         for (int kb = 0; kb < 4; ++kb) {
;           const f32x4 av = ff.vec(kb);
; #pragma unroll
;           for (int j = 0; j < 4; ++j) s[kb][rb][j] = opq(fmaf(s[kb][rb][j], fsc, av[j]));
;         }
;       }
;       if (MODE == 2) {
;         const float c = cl - m[rb];
; #pragma unroll
;         for (int kb = 0; kb < 4; ++kb)
; #pragma unroll
;           for (int j = 0; j < 4; ++j) {
;             const float e = FF::HASVEC ? opq(s[kb][rb][j] + c) : opq(fmaf(s[kb][rb][j], fsc, c));
;             s[kb][rb][j] = opq(fexp2(e) * l[rb]);
;           }
;       } else if (MODE == 0) {
;         float mx = max16(s[0][rb], s[1][rb], s[2][rb], s[3][rb]);
;         mx = xmax16(mx); mx = xmax32(mx);
;         const float cand = FF::HASVEC ? (mx + cl) : fmaf(mx, fsc, cl);
;         if (__builtin_amdgcn_ballot_w64(cand > m[rb] + DEFER_THR) != 0) {
;           const float mn = fmaxf(m[rb], cand);
;           const float alpha = fexp2(m[rb] - mn);
;           m[rb] = mn;
; #pragma unroll
;           for (int db = 0; db < 5; ++db)
; #pragma unroll
;             for (int j = 0; j < 4; ++j) o[db][rb][j] = opq(o[db][rb][j] * alpha);
;         }
.LBB0_548:
	s_or_b64 exec, exec, s[54:55]
	v_or_b32_e32 v80, 47, v197
	v_cmp_le_i32_e32 vcc, v80, v113
	s_and_saveexec_b64 s[54:55], vcc
	s_xor_b64 s[54:55], exec, s[54:55]
	s_cbranch_execz .LBB0_552
	ds_read_b128 v[78:81], v144 offset:16384
	s_waitcnt lgkmcnt(0)
	v_fma_f32 v78, v72, s101, -v78
	v_fma_f32 v77, v73, s101, -v79
	v_fma_f32 v73, v74, s101, -v80
	v_fma_f32 v72, v75, s101, -v81
	ds_read_b128 v[80:83], v144 offset:16448
	s_waitcnt lgkmcnt(0)
	v_fma_f32 v74, v68, s101, -v80
	v_fma_f32 v68, v69, s101, -v81
	v_fma_f32 v69, v70, s101, -v82
	v_fma_f32 v70, v71, s101, -v83
	ds_read_b128 v[80:83], v144 offset:16512
	v_max_f32_e32 v2, v77, v77
	v_max_f32_e32 v3, v78, v78
	s_waitcnt lgkmcnt(0)
	v_fma_f32 v75, v64, s101, -v80
	v_fma_f32 v71, v65, s101, -v81
	v_fma_f32 v65, v66, s101, -v82
	v_fma_f32 v64, v67, s101, -v83
	ds_read_b128 v[80:83], v144 offset:16576
	s_waitcnt lgkmcnt(0)
	v_fma_f32 v66, v60, s101, -v80
	v_fma_f32 v60, v61, s101, -v81
	v_fma_f32 v61, v62, s101, -v82
	v_fma_f32 v62, v63, s101, -v83
	v_max_f32_e32 v2, v3, v2
	v_max3_f32 v3, v72, v74, v68
	v_max3_f32 v67, v71, v65, v64
	v_max3_f32 v79, v66, v60, v61
	s_nop 0
	v_max3_f32 v63, v69, v70, v75
	v_max3_f32 v2, v2, v73, v3
	v_max3_f32 v3, v67, v79, v62
	v_max3_f32 v2, v2, v63, v3
	v_mov_b32_e32 v3, v2
	s_nop 1
	v_permlane16_swap_b32_e32 v2, v3
	v_max_f32_e32 v2, v2, v3
	v_mov_b32_e32 v3, v2
	s_nop 1
	v_permlane32_swap_b32_e32 v2, v3
	v_max_f32_e32 v124, v2, v3
	v_add_f32_e32 v2, v110, v124
	v_add_f32_e32 v3, v111, v125
	v_cmp_gt_f32_e32 vcc, v2, v3
	s_cbranch_vccz .LBB0_551
	v_max_f32_e32 v3, v111, v111
	v_max_f32_e32 v2, v3, v2
	v_sub_f32_e32 v3, v111, v2
	v_exp_f32_e32 v3, v3
	v_mov_b32_e32 v111, v2
	v_mul_f32_e32 v40, v40, v3
	v_mul_f32_e32 v41, v41, v3
	v_mul_f32_e32 v42, v42, v3
	v_mul_f32_e32 v43, v43, v3
	v_mul_f32_e32 v36, v36, v3
	v_mul_f32_e32 v37, v37, v3
	v_mul_f32_e32 v38, v38, v3
	v_mul_f32_e32 v39, v39, v3
	v_mul_f32_e32 v32, v32, v3
	v_mul_f32_e32 v33, v33, v3
	v_mul_f32_e32 v34, v34, v3
	v_mul_f32_e32 v35, v35, v3
	v_mul_f32_e32 v28, v28, v3
	v_mul_f32_e32 v29, v29, v3
	v_mul_f32_e32 v30, v30, v3
	v_mul_f32_e32 v31, v31, v3
	v_mul_f32_e32 v20, v20, v3
	v_mul_f32_e32 v21, v21, v3
	v_mul_f32_e32 v22, v22, v3
	v_mul_f32_e32 v23, v23, v3

; DEVI float opq(float x) { asm("" : "+v"(x)); return x; }
; template <int DK, int MODE, int RBM, class SF, class FF, class POST>
; DEVI void attn_tile_body(const bf16x8 (&qf)[2][DK / 32], const char* Ks, const char* Vs, SF& sf, FF& ff, POST& post,
;                          int cur, int c0, int c1, float (&m)[2], float (&l)[2], f32x4 (&o)[5][2], int fr, int fq) {
;     ...
;   for (int ks = 0; ks < NKC; ++ks)
; #pragma unroll
;     for (int kb = 0; kb < 4; ++kb) {
;       const int koff = DK == 64 ? (kb * 16 + fr) * 128 + (((ks * 4 + fq) ^ (fr & 7)) * 16)
;                                 : (kb * 16 + fr) * 192 + ((ks * 4 + (fq ^ ((fr >> 2) & 3))) * 16);
;       bf16x8 kf = *(const bf16x8*)(Ks + koff);
;       if (RBM & 1) s[kb][0] = __builtin_amdgcn_mfma_f32_16x16x32_bf16(kf, qf[0][ks], s[kb][0], 0, 0, 0);
;       if (RBM & 2) s[kb][1] = __builtin_amdgcn_mfma_f32_16x16x32_bf16(kf, qf[1][ks], s[kb][1], 0, 0, 0);
;     }
; #pragma unroll
;   for (int rb = 0; rb < 2; ++rb) {
;     if (!(RBM & (1 << rb))) continue;
;     const int cm = rb == 0 ? c0 : c1;
;     if (cm == 2) {
;       const float cl = ff.cl(rb, cur);
;       const float fsc = ff.sc;
;       if (FF::HASVEC) {
; #pragma unroll
;         for (int kb = 0; kb < 4; ++kb) {
;           const f32x4 av = ff.vec(kb);
; #pragma unroll
;           for (int j = 0; j < 4; ++j) s[kb][rb][j] = opq(fmaf(s[kb][rb][j], fsc, av[j]));
;         }
;       }
;       if (MODE == 2) {
;         const float c = cl - m[rb];
; #pragma unroll
;         for (int kb = 0; kb < 4; ++kb)
; #pragma unroll
;           for (int j = 0; j < 4; ++j) {
;             const float e = FF::HASVEC ? opq(s[kb][rb][j] + c) : opq(fmaf(s[kb][rb][j], fsc, c));
;             s[kb][rb][j] = opq(fexp2(e) * l[rb]);
;           }
;       } else if (MODE == 0) {
;         float mx = max16(s[0][rb], s[1][rb], s[2][rb], s[3][rb]);
;         mx = xmax16(mx); mx = xmax32(mx);
;         const float cand = FF::HASVEC ? (mx + cl) : fmaf(mx, fsc, cl);
;         if (__builtin_amdgcn_ballot_w64(cand > m[rb] + DEFER_THR) != 0) {
;           const float mn = fmaxf(m[rb], cand);
;           const float alpha = fexp2(m[rb] - mn);
;           m[rb] = mn;
; #pragma unroll
;           for (int db = 0; db < 5; ++db)
; #pragma unroll
;             for (int j = 0; j < 4; ++j) o[db][rb][j] = opq(o[db][rb][j] * alpha);
;         }
.LBB0_557:
	s_or_b64 exec, exec, s[38:39]
	v_cmp_lt_i32_e32 vcc, -1, v143
	s_and_saveexec_b64 s[38:39], vcc
	s_cbranch_execz .LBB0_530
	v_lshrrev_b64 v[2:3], v143, v[118:119]
	v_and_b32_e32 v2, 1, v2
	v_cmp_eq_u32_e32 vcc, 1, v2
	s_and_saveexec_b64 s[54:55], vcc
	s_cbranch_execz .LBB0_529
	v_lshlrev_b32_e32 v196, 6, v143
	s_mul_i32 s6, s42, 0x4100
	v_or_b32_e32 v2, 63, v196
	v_cmp_le_i32_e32 vcc, v2, v113
	v_add_u32_e32 v2, s6, v115
	v_add_u32_e32 v3, v2, v123
	ds_read_b128 v[72:75], v3 offset:20736
	ds_read_b128 v[60:63], v3 offset:16640
	v_add_u32_e32 v2, v2, v134
	ds_read_b128 v[68:71], v3 offset:18688
	v_add_u32_e32 v143, s6, v106
	s_waitcnt lgkmcnt(0)
	v_mfma_f32_16x16x32_bf16 v[80:83], v[72:75], v[8:11], 0
	v_mfma_f32_16x16x32_bf16 v[144:147], v[72:75], v[16:19], 0
	ds_read_b128 v[72:75], v3 offset:22784
	s_waitcnt lgkmcnt(0)
	v_mfma_f32_16x16x32_bf16 v[148:151], v[72:75], v[8:11], 0
	v_mfma_f32_16x16x32_bf16 v[192:195], v[72:75], v[16:19], 0
	ds_read_b128 v[72:75], v2 offset:16640
	v_mfma_f32_16x16x32_bf16 v[64:67], v[60:63], v[8:11], 0
	v_mfma_f32_16x16x32_bf16 v[60:63], v[60:63], v[16:19], 0
	s_waitcnt lgkmcnt(0)
	v_mfma_f32_16x16x32_bf16 v[92:95], v[72:75], v[4:7], v[64:67]
	v_mfma_f32_16x16x32_bf16 v[72:75], v[72:75], v[12:15], v[60:63]
	s_nop 4
	ds_read_b128 v[60:63], v2 offset:18688
	v_mfma_f32_16x16x32_bf16 v[76:79], v[68:71], v[8:11], 0
	v_mfma_f32_16x16x32_bf16 v[68:71], v[68:71], v[16:19], 0
	s_waitcnt lgkmcnt(0)
	v_mfma_f32_16x16x32_bf16 v[88:91], v[60:63], v[4:7], v[76:79]
	v_mfma_f32_16x16x32_bf16 v[68:71], v[60:63], v[12:15], v[68:71]
	ds_read_b128 v[60:63], v2 offset:20736
	s_waitcnt lgkmcnt(0)
	v_mfma_f32_16x16x32_bf16 v[84:87], v[60:63], v[4:7], v[80:83]
	v_mfma_f32_16x16x32_bf16 v[64:67], v[60:63], v[12:15], v[144:147]
	ds_read_b128 v[60:63], v2 offset:22784
	s_waitcnt lgkmcnt(0)
	v_mfma_f32_16x16x32_bf16 v[80:83], v[60:63], v[4:7], v[148:151]
	v_mfma_f32_16x16x32_bf16 v[60:63], v[60:63], v[12:15], v[192:195]
	s_and_saveexec_b64 s[82:83], vcc
	s_xor_b64 s[94:95], exec, s[82:83]
	s_cbranch_execz .LBB0_563
	ds_read_b128 v[76:79], v143 offset:33024
	ds_read_b128 v[146:149], v143 offset:33216
	s_waitcnt lgkmcnt(0)
	v_fma_f32 v145, v92, s101, -v76
	v_fma_f32 v144, v93, s101, -v77
	v_fma_f32 v93, v94, s101, -v78
	v_fma_f32 v92, v95, s101, -v79
	ds_read_b128 v[76:79], v143 offset:33088
	s_waitcnt lgkmcnt(0)
	v_fma_f32 v94, v88, s101, -v76
	v_fma_f32 v88, v89, s101, -v77
	v_fma_f32 v89, v90, s101, -v78
	v_fma_f32 v90, v91, s101, -v79
	s_waitcnt vmcnt(0)
	ds_read_b128 v[76:79], v143 offset:33152
	v_max_f32_e32 v2, v144, v144
	v_max_f32_e32 v3, v145, v145
	s_waitcnt lgkmcnt(0)
	v_fma_f32 v91, v85, s101, -v77
	v_fma_f32 v85, v86, s101, -v78
	v_fma_f32 v86, v80, s101, -v146
	v_fma_f32 v95, v84, s101, -v76
	v_fma_f32 v80, v81, s101, -v147
	v_fma_f32 v84, v87, s101, -v79
	v_fma_f32 v81, v82, s101, -v148
	v_fma_f32 v82, v83, s101, -v149
	v_max_f32_e32 v2, v3, v2
	v_max3_f32 v3, v92, v94, v88
	v_max3_f32 v83, v91, v85, v84
	v_max3_f32 v87, v86, v80, v81
	s_nop 0
	v_max3_f32 v76, v89, v90, v95
	v_max3_f32 v2, v2, v93, v3
	v_max3_f32 v3, v83, v87, v82
	v_max3_f32 v2, v2, v76, v3
	v_mov_b32_e32 v3, v2
	s_nop 1
	v_permlane16_swap_b32_e32 v2, v3
	v_max_f32_e32 v2, v2, v3
	v_mov_b32_e32 v3, v2
	s_nop 1
	v_permlane32_swap_b32_e32 v2, v3
	v_max_f32_e32 v124, v2, v3
	v_add_f32_e32 v2, v108, v124
	v_add_f32_e32 v3, v109, v125
	v_cmp_gt_f32_e32 vcc, v2, v3
	s_cbranch_vccz .LBB0_562
	v_max_f32_e32 v3, v109, v109
	v_max_f32_e32 v2, v3, v2
	v_sub_f32_e32 v3, v109, v2
	v_exp_f32_e32 v3, v3
	v_mov_b32_e32 v109, v2
	v_mul_f32_e32 v56, v56, v3
	v_mul_f32_e32 v57, v57, v3
	v_mul_f32_e32 v58, v58, v3
	v_mul_f32_e32 v59, v59, v3
	v_mul_f32_e32 v52, v52, v3
	v_mul_f32_e32 v53, v53, v3
	v_mul_f32_e32 v54, v54, v3
	v_mul_f32_e32 v55, v55, v3
	v_mul_f32_e32 v48, v48, v3
	v_mul_f32_e32 v49, v49, v3
	v_mul_f32_e32 v50, v50, v3
	v_mul_f32_e32 v51, v51, v3
	v_mul_f32_e32 v44, v44, v3
	v_mul_f32_e32 v45, v45, v3
	v_mul_f32_e32 v46, v46, v3
	v_mul_f32_e32 v47, v47, v3
	v_mul_f32_e32 v24, v24, v3
	v_mul_f32_e32 v25, v25, v3
	v_mul_f32_e32 v26, v26, v3
	v_mul_f32_e32 v27, v27, v3

; DEVI float opq(float x) { asm("" : "+v"(x)); return x; }
; DEVI float fexp2(float x) { return __builtin_amdgcn_exp2f(x); }
; template <int DK, int MODE, int RBM, class SF, class FF, class POST>
; DEVI void attn_tile_body(const bf16x8 (&qf)[2][DK / 32], const char* Ks, const char* Vs, SF& sf, FF& ff, POST& post,
;                          int cur, int c0, int c1, float (&m)[2], float (&l)[2], f32x4 (&o)[5][2], int fr, int fq) {
;     ...
;     if (cm == 2) {
;       const float cl = ff.cl(rb, cur);
;       const float fsc = ff.sc;
;       if (FF::HASVEC) {
; #pragma unroll
;         for (int kb = 0; kb < 4; ++kb) {
;           const f32x4 av = ff.vec(kb);
; #pragma unroll
;           for (int j = 0; j < 4; ++j) s[kb][rb][j] = opq(fmaf(s[kb][rb][j], fsc, av[j]));
;         }
;       }
;       if (MODE == 2) {
;         const float c = cl - m[rb];
; #pragma unroll
;         for (int kb = 0; kb < 4; ++kb)
; #pragma unroll
;           for (int j = 0; j < 4; ++j) {
;             const float e = FF::HASVEC ? opq(s[kb][rb][j] + c) : opq(fmaf(s[kb][rb][j], fsc, c));
;             s[kb][rb][j] = opq(fexp2(e) * l[rb]);
;           }
;       } else if (MODE == 0) {
;         float mx = max16(s[0][rb], s[1][rb], s[2][rb], s[3][rb]);
;         mx = xmax16(mx); mx = xmax32(mx);
;         const float cand = FF::HASVEC ? (mx + cl) : fmaf(mx, fsc, cl);
;         if (__builtin_amdgcn_ballot_w64(cand > m[rb] + DEFER_THR) != 0) {
;           const float mn = fmaxf(m[rb], cand);
;           const float alpha = fexp2(m[rb] - mn);
;           m[rb] = mn;
; #pragma unroll
;           for (int db = 0; db < 5; ++db)
; #pragma unroll
;             for (int j = 0; j < 4; ++j) o[db][rb][j] = opq(o[db][rb][j] * alpha);
;         }
.LBB0_567:
	s_or_b64 exec, exec, s[94:95]
	v_or_b32_e32 v80, 47, v196
	v_cmp_le_i32_e32 vcc, v80, v113
	s_and_saveexec_b64 s[82:83], vcc
	s_xor_b64 s[94:95], exec, s[82:83]
	s_cbranch_execz .LBB0_571
	ds_read_b128 v[78:81], v143 offset:33024
	s_waitcnt lgkmcnt(0)
	v_fma_f32 v78, v72, s101, -v78
	v_fma_f32 v77, v73, s101, -v79
	v_fma_f32 v73, v74, s101, -v80
	v_fma_f32 v72, v75, s101, -v81
	ds_read_b128 v[80:83], v143 offset:33088
	s_waitcnt lgkmcnt(0)
	v_fma_f32 v74, v68, s101, -v80
	v_fma_f32 v68, v69, s101, -v81
	v_fma_f32 v69, v70, s101, -v82
	v_fma_f32 v70, v71, s101, -v83
	ds_read_b128 v[80:83], v143 offset:33152
	v_max_f32_e32 v2, v77, v77
	v_max_f32_e32 v3, v78, v78
	s_waitcnt lgkmcnt(0)
	v_fma_f32 v75, v64, s101, -v80
	v_fma_f32 v71, v65, s101, -v81
	v_fma_f32 v65, v66, s101, -v82
	v_fma_f32 v64, v67, s101, -v83
	ds_read_b128 v[80:83], v143 offset:33216
	s_waitcnt lgkmcnt(0)
	v_fma_f32 v66, v60, s101, -v80
	v_fma_f32 v60, v61, s101, -v81
	v_fma_f32 v61, v62, s101, -v82
	v_fma_f32 v62, v63, s101, -v83
	v_max_f32_e32 v2, v3, v2
	v_max3_f32 v3, v72, v74, v68
	v_max3_f32 v67, v71, v65, v64
	v_max3_f32 v79, v66, v60, v61
	s_nop 0
	v_max3_f32 v63, v69, v70, v75
	v_max3_f32 v2, v2, v73, v3
	v_max3_f32 v3, v67, v79, v62
	v_max3_f32 v2, v2, v63, v3
	v_mov_b32_e32 v3, v2
	s_nop 1
	v_permlane16_swap_b32_e32 v2, v3
	v_max_f32_e32 v2, v2, v3
	v_mov_b32_e32 v3, v2
	s_nop 1
	v_permlane32_swap_b32_e32 v2, v3
	v_max_f32_e32 v124, v2, v3
	v_add_f32_e32 v2, v110, v124
	v_add_f32_e32 v3, v111, v125
	v_cmp_gt_f32_e32 vcc, v2, v3
	s_cbranch_vccz .LBB0_570
	v_max_f32_e32 v3, v111, v111
	v_max_f32_e32 v2, v3, v2
	v_sub_f32_e32 v3, v111, v2
	v_exp_f32_e32 v3, v3
	v_mov_b32_e32 v111, v2
	v_mul_f32_e32 v40, v40, v3
	v_mul_f32_e32 v41, v41, v3
	v_mul_f32_e32 v42, v42, v3
	v_mul_f32_e32 v43, v43, v3
	v_mul_f32_e32 v36, v36, v3
	v_mul_f32_e32 v37, v37, v3
	v_mul_f32_e32 v38, v38, v3
	v_mul_f32_e32 v39, v39, v3
	v_mul_f32_e32 v32, v32, v3
	v_mul_f32_e32 v33, v33, v3
	v_mul_f32_e32 v34, v34, v3
	v_mul_f32_e32 v35, v35, v3
	v_mul_f32_e32 v28, v28, v3
	v_mul_f32_e32 v29, v29, v3
	v_mul_f32_e32 v30, v30, v3
	v_mul_f32_e32 v31, v31, v3
	v_mul_f32_e32 v20, v20, v3
	v_mul_f32_e32 v21, v21, v3
	v_mul_f32_e32 v22, v22, v3
	v_mul_f32_e32 v23, v23, v3
